# hand-written per-mixer output RMSNorm loop (prefetch next rows, batched reductions)
# speedup vs baseline: 1.0137x; 1.0097x over previous
; __device__ __forceinline__ int tid_l() { int t = threadIdx.x; asm volatile("" : "+v"(t)); return t; }
; __device__ __forceinline__ float bf_lo(unsigned w) { return __uint_as_float(w << 16); }
; __device__ __forceinline__ float bf_hi(unsigned w) { return __uint_as_float(w & 0xffff0000u); }
; __device__ __forceinline__ void outnorm_rows(bf16_t* y, const float* og, int bx, int G) {
;     const int tid = tid_l(), lane = tid & 63, wave = tid >> 6;
;     for (int row = (bx * 8 + wave) * 2; row < T; row += G * 16) {
;         u32x4 w[2][4]; float ss[2][3];
; #pragma unroll
;         for (int rr = 0; rr < 2; ++rr)
; #pragma unroll
;             for (int it = 0; it < 4; ++it) w[rr][it] = *(const u32x4*)(y + (size_t)(row + rr) * 2048 + (it * 64 + lane) * 8);
; #pragma unroll
;         for (int rr = 0; rr < 2; ++rr) { ss[rr][0] = 0.f; ss[rr][1] = 0.f; ss[rr][2] = 0.f;
; #pragma unroll
;             for (int it = 0; it < 4; ++it) { const int ch = it * 64 + lane; float s = 0.f;
; #pragma unroll
;                 for (int q = 0; q < 4; ++q) { const float a0 = bf_lo(w[rr][it][q]), a1 = bf_hi(w[rr][it][q]); s += a0 * a0 + a1 * a1; }
;                 const int seg = ch < 96 ? 0 : (ch < 160 ? 1 : 2);
;                 ss[rr][0] += seg == 0 ? s : 0.f; ss[rr][1] += seg == 1 ? s : 0.f; ss[rr][2] += seg == 2 ? s : 0.f; }
;             ss[rr][0] = wave_sum(ss[rr][0]); ss[rr][1] = wave_sum(ss[rr][1]); ss[rr][2] = wave_sum(ss[rr][2]); }
.LBB0_1155:
	s_andn2_b64 vcc, exec, s[28:29]
	s_cbranch_vccnz .LBB0_1227
	v_readlane_b32 s28, v253, 36
	v_readlane_b32 s29, v253, 37
	s_mov_b32 s2, s68
	s_mov_b64 s[34:35], s[20:21]
	s_mov_b32 s0, s28
	s_mov_b64 s[28:29], s[22:23]
	s_waitcnt vmcnt(0)
	v_mov_b32_e32 v0, v175
	s_nop 0
	v_writelane_b32 v255, s0, 24
	v_writelane_b32 v255, s2, 25
	v_writelane_b32 v255, s28, 26
	v_writelane_b32 v255, s29, 27
	v_writelane_b32 v255, s33, 28
	v_writelane_b32 v255, s34, 29
	v_writelane_b32 v255, s35, 30
	v_writelane_b32 v255, s36, 31
	v_writelane_b32 v255, s37, 32
	v_writelane_b32 v255, s38, 33
	v_writelane_b32 v255, s39, 34
	v_writelane_b32 v255, s40, 35
	v_writelane_b32 v255, s41, 36
	v_writelane_b32 v255, s44, 37
	v_writelane_b32 v255, s45, 38
	v_writelane_b32 v255, s46, 39
	v_writelane_b32 v255, s47, 44
	v_writelane_b32 v255, s48, 45
	v_writelane_b32 v255, s49, 46
	v_writelane_b32 v255, s50, 47
	v_writelane_b32 v255, s51, 48
	v_writelane_b32 v255, s52, 49
	v_writelane_b32 v255, s53, 50
	v_writelane_b32 v255, s54, 51
	v_writelane_b32 v255, s55, 52
	v_writelane_b32 v255, s56, 53
	v_writelane_b32 v255, s57, 54
	v_writelane_b32 v255, s58, 55
	v_writelane_b32 v255, s59, 56
	v_writelane_b32 v255, s90, 57
	v_writelane_b32 v255, vcc_lo, 58
	v_writelane_b32 v255, vcc_hi, 59
	s_lshl_b32 s33, s2, 4
	s_lshl_b32 s34, s0, 4
	s_add_u32 s44, s22, 0x9ce8000
	s_addc_u32 s45, s23, 0
	v_readlane_b32 s46, v253, 22
	v_readlane_b32 s47, v253, 23
	s_nop 3
	s_lshl_b32 s28, s30, 13
	s_add_u32 s46, s46, s28
	s_addc_u32 s47, s47, 0
	s_mov_b32 s48, -1
	s_mov_b32 s49, 0
	v_and_b32_e32 v1, 63, v0
	v_lshrrev_b32_e32 v2, 6, v0
	v_lshl_add_u32 v3, v2, 1, s33
	s_nop 1
	v_readfirstlane_b32 s35, v3
	v_lshlrev_b32_e32 v4, 4, v1
	v_lshlrev_b32_e32 v5, 5, v1
	v_add_u32_e32 v6, 0x1000, v5
	global_load_dwordx4 v[72:75], v5, s[46:47]
	global_load_dwordx4 v[76:79], v5, s[46:47] offset:16
	global_load_dwordx4 v[80:83], v5, s[46:47] offset:2048
	global_load_dwordx4 v[84:87], v5, s[46:47] offset:2064
	global_load_dwordx4 v[88:91], v6, s[46:47]
	global_load_dwordx4 v[92:95], v6, s[46:47] offset:16
	global_load_dwordx4 v[96:99], v6, s[46:47] offset:2048
	global_load_dwordx4 v[100:103], v6, s[46:47] offset:2064
	v_xor_b32_e32 v104, 32, v1
	v_lshlrev_b32_e32 v104, 2, v104
	v_xor_b32_e32 v105, 16, v1
	v_lshlrev_b32_e32 v105, 2, v105
	v_xor_b32_e32 v106, 8, v1
	v_lshlrev_b32_e32 v106, 2, v106
	v_xor_b32_e32 v107, 4, v1
	v_lshlrev_b32_e32 v107, 2, v107
	v_xor_b32_e32 v108, 2, v1
	v_lshlrev_b32_e32 v108, 2, v108
	v_xor_b32_e32 v109, 1, v1
	v_lshlrev_b32_e32 v109, 2, v109
	s_cmp_ge_u32 s35, 0x6000
	s_cbranch_scc1 .Lon_done
	v_lshl_add_u32 v7, s35, 12, v4
	v_add_u32_e32 v110, 0x1000, v7
	global_load_dwordx4 v[8:11], v7, s[44:45]
	global_load_dwordx4 v[12:15], v7, s[44:45] offset:1024
	global_load_dwordx4 v[16:19], v7, s[44:45] offset:2048
	global_load_dwordx4 v[20:23], v7, s[44:45] offset:3072
	global_load_dwordx4 v[24:27], v110, s[44:45]
	global_load_dwordx4 v[28:31], v110, s[44:45] offset:1024
	global_load_dwordx4 v[32:35], v110, s[44:45] offset:2048
	global_load_dwordx4 v[36:39], v110, s[44:45] offset:3072
.Lon_loop:
	s_add_i32 s28, s35, s34
	s_cmp_lt_u32 s28, 0x6000
	s_cselect_b32 s29, s28, s35
	v_lshl_add_u32 v5, s29, 12, v4
	v_add_u32_e32 v6, 0x1000, v5
	global_load_dwordx4 v[40:43], v5, s[44:45]
	global_load_dwordx4 v[44:47], v5, s[44:45] offset:1024
	global_load_dwordx4 v[48:51], v5, s[44:45] offset:2048
	global_load_dwordx4 v[52:55], v5, s[44:45] offset:3072
	global_load_dwordx4 v[56:59], v6, s[44:45]
	global_load_dwordx4 v[60:63], v6, s[44:45] offset:1024
	global_load_dwordx4 v[64:67], v6, s[44:45] offset:2048
	global_load_dwordx4 v[68:71], v6, s[44:45] offset:3072
	s_waitcnt vmcnt(8)
	v_lshlrev_b32_e32 v111, 16, v8
	v_and_b32_e32 v112, 0xffff0000, v8
	v_mul_f32_e32 v113, v111, v111
	v_fmac_f32_e32 v113, v112, v112
	v_lshlrev_b32_e32 v111, 16, v9
	v_and_b32_e32 v112, 0xffff0000, v9
	v_fmac_f32_e32 v113, v111, v111
	v_fmac_f32_e32 v113, v112, v112
	v_lshlrev_b32_e32 v111, 16, v10
	v_and_b32_e32 v112, 0xffff0000, v10
	v_fmac_f32_e32 v113, v111, v111
	v_fmac_f32_e32 v113, v112, v112
	v_lshlrev_b32_e32 v111, 16, v11
	v_and_b32_e32 v112, 0xffff0000, v11
	v_fmac_f32_e32 v113, v111, v111
	v_fmac_f32_e32 v113, v112, v112
	v_lshlrev_b32_e32 v111, 16, v12
	v_and_b32_e32 v112, 0xffff0000, v12
	v_mul_f32_e32 v114, v111, v111
	v_fmac_f32_e32 v114, v112, v112
	v_lshlrev_b32_e32 v111, 16, v13
	v_and_b32_e32 v112, 0xffff0000, v13
	v_fmac_f32_e32 v114, v111, v111
	v_fmac_f32_e32 v114, v112, v112
	v_lshlrev_b32_e32 v111, 16, v14
	v_and_b32_e32 v112, 0xffff0000, v14
	v_fmac_f32_e32 v114, v111, v111
	v_fmac_f32_e32 v114, v112, v112
	v_lshlrev_b32_e32 v111, 16, v15
	v_and_b32_e32 v112, 0xffff0000, v15
	v_fmac_f32_e32 v114, v111, v111
	v_fmac_f32_e32 v114, v112, v112
	v_lshlrev_b32_e32 v111, 16, v16
	v_and_b32_e32 v112, 0xffff0000, v16
	v_mul_f32_e32 v115, v111, v111
	v_fmac_f32_e32 v115, v112, v112
	v_lshlrev_b32_e32 v111, 16, v17
	v_and_b32_e32 v112, 0xffff0000, v17
	v_fmac_f32_e32 v115, v111, v111
	v_fmac_f32_e32 v115, v112, v112
	v_lshlrev_b32_e32 v111, 16, v18
	v_and_b32_e32 v112, 0xffff0000, v18
	v_fmac_f32_e32 v115, v111, v111
	v_fmac_f32_e32 v115, v112, v112
	v_lshlrev_b32_e32 v111, 16, v19
	v_and_b32_e32 v112, 0xffff0000, v19
	v_fmac_f32_e32 v115, v111, v111
	v_fmac_f32_e32 v115, v112, v112
	v_lshlrev_b32_e32 v111, 16, v20
	v_and_b32_e32 v112, 0xffff0000, v20
	v_mul_f32_e32 v116, v111, v111
	v_fmac_f32_e32 v116, v112, v112
	v_lshlrev_b32_e32 v111, 16, v21
	v_and_b32_e32 v112, 0xffff0000, v21
	v_fmac_f32_e32 v116, v111, v111
	v_fmac_f32_e32 v116, v112, v112
	v_lshlrev_b32_e32 v111, 16, v22
; __device__ __forceinline__ float bf_lo(unsigned w) { return __uint_as_float(w << 16); }
; __device__ __forceinline__ float bf_hi(unsigned w) { return __uint_as_float(w & 0xffff0000u); }
; __device__ __forceinline__ void outnorm_rows(bf16_t* y, const float* og, int bx, int G) {
;     ...
;         for (int rr = 0; rr < 2; ++rr) { ss[rr][0] = 0.f; ss[rr][1] = 0.f; ss[rr][2] = 0.f;
; #pragma unroll
;             for (int it = 0; it < 4; ++it) { const int ch = it * 64 + lane; float s = 0.f;
; #pragma unroll
;                 for (int q = 0; q < 4; ++q) { const float a0 = bf_lo(w[rr][it][q]), a1 = bf_hi(w[rr][it][q]); s += a0 * a0 + a1 * a1; }
;                 const int seg = ch < 96 ? 0 : (ch < 160 ? 1 : 2);
;                 ss[rr][0] += seg == 0 ? s : 0.f; ss[rr][1] += seg == 1 ? s : 0.f; ss[rr][2] += seg == 2 ? s : 0.f; }
;             ss[rr][0] = wave_sum(ss[rr][0]); ss[rr][1] = wave_sum(ss[rr][1]); ss[rr][2] = wave_sum(ss[rr][2]); }
	v_and_b32_e32 v112, 0xffff0000, v22
	v_fmac_f32_e32 v116, v111, v111
	v_fmac_f32_e32 v116, v112, v112
	v_lshlrev_b32_e32 v111, 16, v23
	v_and_b32_e32 v112, 0xffff0000, v23
	v_fmac_f32_e32 v116, v111, v111
	v_fmac_f32_e32 v116, v112, v112
	v_cndmask_b32_e64 v111, 0, v114, s[48:49]
	v_sub_f32_e32 v112, v114, v111
	v_add_f32_e32 v117, v113, v111
	v_cndmask_b32_e64 v111, 0, v115, s[48:49]
	v_add_f32_e32 v118, v112, v111
	v_sub_f32_e32 v111, v115, v111
	v_add_f32_e32 v119, v111, v116
	v_lshlrev_b32_e32 v111, 16, v24
	v_and_b32_e32 v112, 0xffff0000, v24
	v_mul_f32_e32 v113, v111, v111
	v_fmac_f32_e32 v113, v112, v112
	v_lshlrev_b32_e32 v111, 16, v25
	v_and_b32_e32 v112, 0xffff0000, v25
	v_fmac_f32_e32 v113, v111, v111
	v_fmac_f32_e32 v113, v112, v112
	v_lshlrev_b32_e32 v111, 16, v26
	v_and_b32_e32 v112, 0xffff0000, v26
	v_fmac_f32_e32 v113, v111, v111
	v_fmac_f32_e32 v113, v112, v112
	v_lshlrev_b32_e32 v111, 16, v27
	v_and_b32_e32 v112, 0xffff0000, v27
	v_fmac_f32_e32 v113, v111, v111
	v_fmac_f32_e32 v113, v112, v112
	v_lshlrev_b32_e32 v111, 16, v28
	v_and_b32_e32 v112, 0xffff0000, v28
	v_mul_f32_e32 v114, v111, v111
	v_fmac_f32_e32 v114, v112, v112
	v_lshlrev_b32_e32 v111, 16, v29
	v_and_b32_e32 v112, 0xffff0000, v29
	v_fmac_f32_e32 v114, v111, v111
	v_fmac_f32_e32 v114, v112, v112
	v_lshlrev_b32_e32 v111, 16, v30
	v_and_b32_e32 v112, 0xffff0000, v30
	v_fmac_f32_e32 v114, v111, v111
	v_fmac_f32_e32 v114, v112, v112
	v_lshlrev_b32_e32 v111, 16, v31
	v_and_b32_e32 v112, 0xffff0000, v31
	v_fmac_f32_e32 v114, v111, v111
	v_fmac_f32_e32 v114, v112, v112
	v_lshlrev_b32_e32 v111, 16, v32
	v_and_b32_e32 v112, 0xffff0000, v32
	v_mul_f32_e32 v115, v111, v111
	v_fmac_f32_e32 v115, v112, v112
	v_lshlrev_b32_e32 v111, 16, v33
	v_and_b32_e32 v112, 0xffff0000, v33
	v_fmac_f32_e32 v115, v111, v111
	v_fmac_f32_e32 v115, v112, v112
	v_lshlrev_b32_e32 v111, 16, v34
	v_and_b32_e32 v112, 0xffff0000, v34
	v_fmac_f32_e32 v115, v111, v111
	v_fmac_f32_e32 v115, v112, v112
	v_lshlrev_b32_e32 v111, 16, v35
	v_and_b32_e32 v112, 0xffff0000, v35
	v_fmac_f32_e32 v115, v111, v111
	v_fmac_f32_e32 v115, v112, v112
	v_lshlrev_b32_e32 v111, 16, v36
	v_and_b32_e32 v112, 0xffff0000, v36
	v_mul_f32_e32 v116, v111, v111
	v_fmac_f32_e32 v116, v112, v112
	v_lshlrev_b32_e32 v111, 16, v37
	v_and_b32_e32 v112, 0xffff0000, v37
	v_fmac_f32_e32 v116, v111, v111
	v_fmac_f32_e32 v116, v112, v112
	v_lshlrev_b32_e32 v111, 16, v38
	v_and_b32_e32 v112, 0xffff0000, v38
	v_fmac_f32_e32 v116, v111, v111
	v_fmac_f32_e32 v116, v112, v112
	v_lshlrev_b32_e32 v111, 16, v39
	v_and_b32_e32 v112, 0xffff0000, v39
	v_fmac_f32_e32 v116, v111, v111
	v_fmac_f32_e32 v116, v112, v112
	v_cndmask_b32_e64 v111, 0, v114, s[48:49]
	v_sub_f32_e32 v112, v114, v111
	v_add_f32_e32 v120, v113, v111
	v_cndmask_b32_e64 v111, 0, v115, s[48:49]
	v_add_f32_e32 v121, v112, v111
	v_sub_f32_e32 v111, v115, v111
	v_add_f32_e32 v122, v111, v116
	ds_bpermute_b32 v123, v104, v117
	ds_bpermute_b32 v124, v104, v118
	ds_bpermute_b32 v125, v104, v119
	ds_bpermute_b32 v126, v104, v120
	ds_bpermute_b32 v127, v104, v121
	ds_bpermute_b32 v2, v104, v122
	s_waitcnt lgkmcnt(0)
	v_add_f32_e32 v117, v117, v123
	v_add_f32_e32 v118, v118, v124
	v_add_f32_e32 v119, v119, v125
	v_add_f32_e32 v120, v120, v126
	v_add_f32_e32 v121, v121, v127
	v_add_f32_e32 v122, v122, v2
	ds_bpermute_b32 v123, v105, v117
	ds_bpermute_b32 v124, v105, v118
	ds_bpermute_b32 v125, v105, v119
	ds_bpermute_b32 v126, v105, v120
	ds_bpermute_b32 v127, v105, v121
	ds_bpermute_b32 v2, v105, v122
	s_waitcnt lgkmcnt(0)
	v_add_f32_e32 v117, v117, v123
	v_add_f32_e32 v118, v118, v124
	v_add_f32_e32 v119, v119, v125
	v_add_f32_e32 v120, v120, v126
	v_add_f32_e32 v121, v121, v127
	v_add_f32_e32 v122, v122, v2
	ds_bpermute_b32 v123, v106, v117
	ds_bpermute_b32 v124, v106, v118
	ds_bpermute_b32 v125, v106, v119
	ds_bpermute_b32 v126, v106, v120
	ds_bpermute_b32 v127, v106, v121
	ds_bpermute_b32 v2, v106, v122
	s_waitcnt lgkmcnt(0)
	v_add_f32_e32 v117, v117, v123
	v_add_f32_e32 v118, v118, v124
	v_add_f32_e32 v119, v119, v125
	v_add_f32_e32 v120, v120, v126
	v_add_f32_e32 v121, v121, v127
	v_add_f32_e32 v122, v122, v2
	ds_bpermute_b32 v123, v107, v117
	ds_bpermute_b32 v124, v107, v118
	ds_bpermute_b32 v125, v107, v119
	ds_bpermute_b32 v126, v107, v120
	ds_bpermute_b32 v127, v107, v121
	ds_bpermute_b32 v2, v107, v122
	s_waitcnt lgkmcnt(0)
	v_add_f32_e32 v117, v117, v123
	v_add_f32_e32 v118, v118, v124
	v_add_f32_e32 v119, v119, v125
	v_add_f32_e32 v120, v120, v126
	v_add_f32_e32 v121, v121, v127
	v_add_f32_e32 v122, v122, v2
	ds_bpermute_b32 v123, v108, v117
	ds_bpermute_b32 v124, v108, v118
	ds_bpermute_b32 v125, v108, v119
	ds_bpermute_b32 v126, v108, v120
	ds_bpermute_b32 v127, v108, v121
	ds_bpermute_b32 v2, v108, v122
	s_waitcnt lgkmcnt(0)
	v_add_f32_e32 v117, v117, v123
	v_add_f32_e32 v118, v118, v124
	v_add_f32_e32 v119, v119, v125
	v_add_f32_e32 v120, v120, v126
	v_add_f32_e32 v121, v121, v127
	v_add_f32_e32 v122, v122, v2
	ds_bpermute_b32 v123, v109, v117
	ds_bpermute_b32 v124, v109, v118
	ds_bpermute_b32 v125, v109, v119
	ds_bpermute_b32 v126, v109, v120
	ds_bpermute_b32 v127, v109, v121
	ds_bpermute_b32 v2, v109, v122
	s_waitcnt lgkmcnt(0)
; __device__ __forceinline__ unsigned cvt_pk_bf16(float lo, float hi) { unsigned r; asm("v_cvt_pk_bf16_f32 %0, %1, %2" : "=v"(r) : "v"(lo), "v"(hi)); return r; }
; __device__ __forceinline__ float bf_lo(unsigned w) { return __uint_as_float(w << 16); }
; __device__ __forceinline__ float bf_hi(unsigned w) { return __uint_as_float(w & 0xffff0000u); }
; __device__ __forceinline__ void outnorm_rows(bf16_t* y, const float* og, int bx, int G) {
;     ...
; #pragma unroll
;         for (int rr = 0; rr < 2; ++rr) {
;             const float r0 = 1.0f / sqrtf(ss[rr][0] * (1.0f / 768.0f) + EPS), r1 = 1.0f / sqrtf(ss[rr][1] * (1.0f / 512.0f) + EPS), r2 = 1.0f / sqrtf(ss[rr][2] * (1.0f / 768.0f) + EPS);
; #pragma unroll
;             for (int it = 0; it < 4; ++it) { const int ch = it * 64 + lane; const float r = ch < 96 ? r0 : (ch < 160 ? r1 : r2);
;                 const f32x4 g0 = *(const f32x4*)(og + ch * 8), g1 = *(const f32x4*)(og + ch * 8 + 4);
;                 const u32x4 ww = w[rr][it];
;                 u32x4 o; o.x = cvt_pk_bf16(bf_lo(ww.x) * r * g0[0], bf_hi(ww.x) * r * g0[1]); o.y = cvt_pk_bf16(bf_lo(ww.y) * r * g0[2], bf_hi(ww.y) * r * g0[3]);
;                 o.z = cvt_pk_bf16(bf_lo(ww.z) * r * g1[0], bf_hi(ww.z) * r * g1[1]); o.w = cvt_pk_bf16(bf_lo(ww.w) * r * g1[2], bf_hi(ww.w) * r * g1[3]);
;                 *(u32x4*)(y + (size_t)(row + rr) * 2048 + ch * 8) = o; } }
	v_add_f32_e32 v117, v117, v123
	v_add_f32_e32 v118, v118, v124
	v_add_f32_e32 v119, v119, v125
	v_add_f32_e32 v120, v120, v126
	v_add_f32_e32 v121, v121, v127
	v_add_f32_e32 v122, v122, v2
	v_fmamk_f32 v117, v117, 0x3aaaaaab, v222
	v_fmamk_f32 v118, v118, 0x3b000000, v222
	v_fmamk_f32 v119, v119, 0x3aaaaaab, v222
	v_fmamk_f32 v120, v120, 0x3aaaaaab, v222
	v_fmamk_f32 v121, v121, 0x3b000000, v222
	v_fmamk_f32 v122, v122, 0x3aaaaaab, v222
	v_mov_b32_e32 v111, v117
	v_cmp_eq_u32_e32 vcc, 1, v1
	s_nop 1
	v_cndmask_b32_e32 v111, v111, v118, vcc
	v_cmp_eq_u32_e32 vcc, 2, v1
	s_nop 1
	v_cndmask_b32_e32 v111, v111, v119, vcc
	v_cmp_eq_u32_e32 vcc, 3, v1
	s_nop 1
	v_cndmask_b32_e32 v111, v111, v120, vcc
	v_cmp_eq_u32_e32 vcc, 4, v1
	s_nop 1
	v_cndmask_b32_e32 v111, v111, v121, vcc
	v_cmp_eq_u32_e32 vcc, 5, v1
	s_nop 1
	v_cndmask_b32_e32 v111, v111, v122, vcc
	v_cmp_gt_f32_e32 vcc, s89, v111
	v_mul_f32_e32 v112, 0x4f800000, v111
	s_nop 0
	v_cndmask_b32_e32 v111, v111, v112, vcc
	v_sqrt_f32_e32 v112, v111
	s_nop 0
	v_add_u32_e32 v113, -1, v112
	v_fma_f32 v114, -v113, v112, v111
	v_cmp_ge_f32_e64 s[50:51], 0, v114
	v_add_u32_e32 v114, 1, v112
	s_nop 0
	v_cndmask_b32_e64 v113, v112, v113, s[50:51]
	v_fma_f32 v112, -v114, v112, v111
	v_cmp_lt_f32_e64 s[50:51], 0, v112
	s_nop 1
	v_cndmask_b32_e64 v112, v113, v114, s[50:51]
	v_mul_f32_e32 v113, 0x37800000, v112
	v_cndmask_b32_e32 v112, v112, v113, vcc
	v_cmp_class_f32_e32 vcc, v111, v223
	s_nop 1
	v_cndmask_b32_e32 v111, v112, v111, vcc
	v_div_scale_f32 v112, s[50:51], v111, v111, 1.0
	v_rcp_f32_e32 v113, v112
	s_nop 0
	v_fma_f32 v114, -v112, v113, 1.0
	v_fmac_f32_e32 v113, v114, v113
	v_div_scale_f32 v114, vcc, 1.0, v111, 1.0
	v_mul_f32_e32 v115, v114, v113
	v_fma_f32 v116, -v112, v115, v114
	v_fmac_f32_e32 v115, v116, v113
	v_fma_f32 v112, -v112, v115, v114
	v_div_fmas_f32 v112, v112, v113, v115
	v_div_fixup_f32 v123, v112, v111, 1.0
	s_nop 1
	v_readlane_b32 s36, v123, 0
	v_readlane_b32 s37, v123, 1
	v_readlane_b32 s38, v123, 2
	v_readlane_b32 s39, v123, 3
	v_readlane_b32 s40, v123, 4
	v_readlane_b32 s41, v123, 5
	s_nop 3
	v_mov_b32_e32 v124, s37
	v_mov_b32_e32 v126, s36
	v_cndmask_b32_e64 v124, v124, v126, s[48:49]
	v_mov_b32_e32 v125, s38
	v_mov_b32_e32 v126, s37
	v_cndmask_b32_e64 v125, v125, v126, s[48:49]
	v_lshlrev_b32_e32 v111, 16, v8
	v_and_b32_e32 v112, 0xffff0000, v8
	v_mul_f32_e32 v111, s36, v111
	v_mul_f32_e32 v112, s36, v112
	v_mul_f32_e32 v111, v111, v72
	v_mul_f32_e32 v112, v112, v73
	v_cvt_pk_bf16_f32 v8, v111, v112
	v_lshlrev_b32_e32 v111, 16, v9
	v_and_b32_e32 v112, 0xffff0000, v9
	v_mul_f32_e32 v111, s36, v111
	v_mul_f32_e32 v112, s36, v112
	v_mul_f32_e32 v111, v111, v74
	v_mul_f32_e32 v112, v112, v75
	v_cvt_pk_bf16_f32 v9, v111, v112
	v_lshlrev_b32_e32 v111, 16, v10
	v_and_b32_e32 v112, 0xffff0000, v10
	v_mul_f32_e32 v111, s36, v111
	v_mul_f32_e32 v112, s36, v112
	v_mul_f32_e32 v111, v111, v76
	v_mul_f32_e32 v112, v112, v77
	v_cvt_pk_bf16_f32 v10, v111, v112
	v_lshlrev_b32_e32 v111, 16, v11
	v_and_b32_e32 v112, 0xffff0000, v11
	v_mul_f32_e32 v111, s36, v111
	v_mul_f32_e32 v112, s36, v112
	v_mul_f32_e32 v111, v111, v78
	v_mul_f32_e32 v112, v112, v79
	v_cvt_pk_bf16_f32 v11, v111, v112
	global_store_dwordx4 v7, v[8:11], s[44:45]
	v_lshlrev_b32_e32 v111, 16, v12
	v_and_b32_e32 v112, 0xffff0000, v12
	v_mul_f32_e32 v111, v124, v111
	v_mul_f32_e32 v112, v124, v112
	v_mul_f32_e32 v111, v111, v80
	v_mul_f32_e32 v112, v112, v81
	v_cvt_pk_bf16_f32 v12, v111, v112
	v_lshlrev_b32_e32 v111, 16, v13
	v_and_b32_e32 v112, 0xffff0000, v13
	v_mul_f32_e32 v111, v124, v111
	v_mul_f32_e32 v112, v124, v112
	v_mul_f32_e32 v111, v111, v82
	v_mul_f32_e32 v112, v112, v83
	v_cvt_pk_bf16_f32 v13, v111, v112
	v_lshlrev_b32_e32 v111, 16, v14
	v_and_b32_e32 v112, 0xffff0000, v14
	v_mul_f32_e32 v111, v124, v111
	v_mul_f32_e32 v112, v124, v112
	v_mul_f32_e32 v111, v111, v84
	v_mul_f32_e32 v112, v112, v85
	v_cvt_pk_bf16_f32 v14, v111, v112
	v_lshlrev_b32_e32 v111, 16, v15
	v_and_b32_e32 v112, 0xffff0000, v15
	v_mul_f32_e32 v111, v124, v111
	v_mul_f32_e32 v112, v124, v112
	v_mul_f32_e32 v111, v111, v86
	v_mul_f32_e32 v112, v112, v87
	v_cvt_pk_bf16_f32 v15, v111, v112
	global_store_dwordx4 v7, v[12:15], s[44:45] offset:1024
	v_lshlrev_b32_e32 v111, 16, v16
	v_and_b32_e32 v112, 0xffff0000, v16
	v_mul_f32_e32 v111, v125, v111
	v_mul_f32_e32 v112, v125, v112
	v_mul_f32_e32 v111, v111, v88
	v_mul_f32_e32 v112, v112, v89
	v_cvt_pk_bf16_f32 v16, v111, v112
	v_lshlrev_b32_e32 v111, 16, v17
	v_and_b32_e32 v112, 0xffff0000, v17
	v_mul_f32_e32 v111, v125, v111
	v_mul_f32_e32 v112, v125, v112
	v_mul_f32_e32 v111, v111, v90
	v_mul_f32_e32 v112, v112, v91
	v_cvt_pk_bf16_f32 v17, v111, v112
	v_lshlrev_b32_e32 v111, 16, v18
	v_and_b32_e32 v112, 0xffff0000, v18
	v_mul_f32_e32 v111, v125, v111
	v_mul_f32_e32 v112, v125, v112
	v_mul_f32_e32 v111, v111, v92
	v_mul_f32_e32 v112, v112, v93
	v_cvt_pk_bf16_f32 v18, v111, v112
	v_lshlrev_b32_e32 v111, 16, v19
	v_and_b32_e32 v112, 0xffff0000, v19
	v_mul_f32_e32 v111, v125, v111
	v_mul_f32_e32 v112, v125, v112
	v_mul_f32_e32 v111, v111, v94
	v_mul_f32_e32 v112, v112, v95
	v_cvt_pk_bf16_f32 v19, v111, v112
	global_store_dwordx4 v7, v[16:19], s[44:45] offset:2048
	v_lshlrev_b32_e32 v111, 16, v20
	v_and_b32_e32 v112, 0xffff0000, v20
	v_mul_f32_e32 v111, s38, v111
	v_mul_f32_e32 v112, s38, v112
	v_mul_f32_e32 v111, v111, v96
	v_mul_f32_e32 v112, v112, v97
	v_cvt_pk_bf16_f32 v20, v111, v112
	v_lshlrev_b32_e32 v111, 16, v21
	v_and_b32_e32 v112, 0xffff0000, v21
	v_mul_f32_e32 v111, s38, v111
	v_mul_f32_e32 v112, s38, v112
	v_mul_f32_e32 v111, v111, v98
	v_mul_f32_e32 v112, v112, v99
; __device__ __forceinline__ unsigned cvt_pk_bf16(float lo, float hi) { unsigned r; asm("v_cvt_pk_bf16_f32 %0, %1, %2" : "=v"(r) : "v"(lo), "v"(hi)); return r; }
; __device__ __forceinline__ float bf_lo(unsigned w) { return __uint_as_float(w << 16); }
; __device__ __forceinline__ float bf_hi(unsigned w) { return __uint_as_float(w & 0xffff0000u); }
; __device__ __forceinline__ void outnorm_rows(bf16_t* y, const float* og, int bx, int G) {
;     ...
;         for (int rr = 0; rr < 2; ++rr) {
;             const float r0 = 1.0f / sqrtf(ss[rr][0] * (1.0f / 768.0f) + EPS), r1 = 1.0f / sqrtf(ss[rr][1] * (1.0f / 512.0f) + EPS), r2 = 1.0f / sqrtf(ss[rr][2] * (1.0f / 768.0f) + EPS);
; #pragma unroll
;             for (int it = 0; it < 4; ++it) { const int ch = it * 64 + lane; const float r = ch < 96 ? r0 : (ch < 160 ? r1 : r2);
;                 const f32x4 g0 = *(const f32x4*)(og + ch * 8), g1 = *(const f32x4*)(og + ch * 8 + 4);
;                 const u32x4 ww = w[rr][it];
;                 u32x4 o; o.x = cvt_pk_bf16(bf_lo(ww.x) * r * g0[0], bf_hi(ww.x) * r * g0[1]); o.y = cvt_pk_bf16(bf_lo(ww.y) * r * g0[2], bf_hi(ww.y) * r * g0[3]);
;                 o.z = cvt_pk_bf16(bf_lo(ww.z) * r * g1[0], bf_hi(ww.z) * r * g1[1]); o.w = cvt_pk_bf16(bf_lo(ww.w) * r * g1[2], bf_hi(ww.w) * r * g1[3]);
;                 *(u32x4*)(y + (size_t)(row + rr) * 2048 + ch * 8) = o; } }
	v_cvt_pk_bf16_f32 v21, v111, v112
	v_lshlrev_b32_e32 v111, 16, v22
	v_and_b32_e32 v112, 0xffff0000, v22
	v_mul_f32_e32 v111, s38, v111
	v_mul_f32_e32 v112, s38, v112
	v_mul_f32_e32 v111, v111, v100
	v_mul_f32_e32 v112, v112, v101
	v_cvt_pk_bf16_f32 v22, v111, v112
	v_lshlrev_b32_e32 v111, 16, v23
	v_and_b32_e32 v112, 0xffff0000, v23
	v_mul_f32_e32 v111, s38, v111
	v_mul_f32_e32 v112, s38, v112
	v_mul_f32_e32 v111, v111, v102
	v_mul_f32_e32 v112, v112, v103
	v_cvt_pk_bf16_f32 v23, v111, v112
	global_store_dwordx4 v7, v[20:23], s[44:45] offset:3072
	v_mov_b32_e32 v124, s40
	v_mov_b32_e32 v126, s39
	v_cndmask_b32_e64 v124, v124, v126, s[48:49]
	v_mov_b32_e32 v125, s41
	v_mov_b32_e32 v126, s40
	v_cndmask_b32_e64 v125, v125, v126, s[48:49]
	v_lshlrev_b32_e32 v111, 16, v24
	v_and_b32_e32 v112, 0xffff0000, v24
	v_mul_f32_e32 v111, s39, v111
	v_mul_f32_e32 v112, s39, v112
	v_mul_f32_e32 v111, v111, v72
	v_mul_f32_e32 v112, v112, v73
	v_cvt_pk_bf16_f32 v24, v111, v112
	v_lshlrev_b32_e32 v111, 16, v25
	v_and_b32_e32 v112, 0xffff0000, v25
	v_mul_f32_e32 v111, s39, v111
	v_mul_f32_e32 v112, s39, v112
	v_mul_f32_e32 v111, v111, v74
	v_mul_f32_e32 v112, v112, v75
	v_cvt_pk_bf16_f32 v25, v111, v112
	v_lshlrev_b32_e32 v111, 16, v26
	v_and_b32_e32 v112, 0xffff0000, v26
	v_mul_f32_e32 v111, s39, v111
	v_mul_f32_e32 v112, s39, v112
	v_mul_f32_e32 v111, v111, v76
	v_mul_f32_e32 v112, v112, v77
	v_cvt_pk_bf16_f32 v26, v111, v112
	v_lshlrev_b32_e32 v111, 16, v27
	v_and_b32_e32 v112, 0xffff0000, v27
	v_mul_f32_e32 v111, s39, v111
	v_mul_f32_e32 v112, s39, v112
	v_mul_f32_e32 v111, v111, v78
	v_mul_f32_e32 v112, v112, v79
	v_cvt_pk_bf16_f32 v27, v111, v112
	global_store_dwordx4 v110, v[24:27], s[44:45]
	v_lshlrev_b32_e32 v111, 16, v28
	v_and_b32_e32 v112, 0xffff0000, v28
	v_mul_f32_e32 v111, v124, v111
	v_mul_f32_e32 v112, v124, v112
	v_mul_f32_e32 v111, v111, v80
	v_mul_f32_e32 v112, v112, v81
	v_cvt_pk_bf16_f32 v28, v111, v112
	v_lshlrev_b32_e32 v111, 16, v29
	v_and_b32_e32 v112, 0xffff0000, v29
	v_mul_f32_e32 v111, v124, v111
	v_mul_f32_e32 v112, v124, v112
	v_mul_f32_e32 v111, v111, v82
	v_mul_f32_e32 v112, v112, v83
	v_cvt_pk_bf16_f32 v29, v111, v112
	v_lshlrev_b32_e32 v111, 16, v30
	v_and_b32_e32 v112, 0xffff0000, v30
	v_mul_f32_e32 v111, v124, v111
	v_mul_f32_e32 v112, v124, v112
	v_mul_f32_e32 v111, v111, v84
	v_mul_f32_e32 v112, v112, v85
	v_cvt_pk_bf16_f32 v30, v111, v112
	v_lshlrev_b32_e32 v111, 16, v31
	v_and_b32_e32 v112, 0xffff0000, v31
	v_mul_f32_e32 v111, v124, v111
	v_mul_f32_e32 v112, v124, v112
	v_mul_f32_e32 v111, v111, v86
	v_mul_f32_e32 v112, v112, v87
	v_cvt_pk_bf16_f32 v31, v111, v112
	global_store_dwordx4 v110, v[28:31], s[44:45] offset:1024
	v_lshlrev_b32_e32 v111, 16, v32
	v_and_b32_e32 v112, 0xffff0000, v32
	v_mul_f32_e32 v111, v125, v111
	v_mul_f32_e32 v112, v125, v112
	v_mul_f32_e32 v111, v111, v88
	v_mul_f32_e32 v112, v112, v89
	v_cvt_pk_bf16_f32 v32, v111, v112
	v_lshlrev_b32_e32 v111, 16, v33
	v_and_b32_e32 v112, 0xffff0000, v33
	v_mul_f32_e32 v111, v125, v111
	v_mul_f32_e32 v112, v125, v112
	v_mul_f32_e32 v111, v111, v90
	v_mul_f32_e32 v112, v112, v91
	v_cvt_pk_bf16_f32 v33, v111, v112
	v_lshlrev_b32_e32 v111, 16, v34
	v_and_b32_e32 v112, 0xffff0000, v34
	v_mul_f32_e32 v111, v125, v111
	v_mul_f32_e32 v112, v125, v112
	v_mul_f32_e32 v111, v111, v92
	v_mul_f32_e32 v112, v112, v93
	v_cvt_pk_bf16_f32 v34, v111, v112
	v_lshlrev_b32_e32 v111, 16, v35
	v_and_b32_e32 v112, 0xffff0000, v35
	v_mul_f32_e32 v111, v125, v111
	v_mul_f32_e32 v112, v125, v112
	v_mul_f32_e32 v111, v111, v94
	v_mul_f32_e32 v112, v112, v95
	v_cvt_pk_bf16_f32 v35, v111, v112
	global_store_dwordx4 v110, v[32:35], s[44:45] offset:2048
	v_lshlrev_b32_e32 v111, 16, v36
	v_and_b32_e32 v112, 0xffff0000, v36
	v_mul_f32_e32 v111, s41, v111
	v_mul_f32_e32 v112, s41, v112
	v_mul_f32_e32 v111, v111, v96
	v_mul_f32_e32 v112, v112, v97
	v_cvt_pk_bf16_f32 v36, v111, v112
	v_lshlrev_b32_e32 v111, 16, v37
	v_and_b32_e32 v112, 0xffff0000, v37
	v_mul_f32_e32 v111, s41, v111
	v_mul_f32_e32 v112, s41, v112
	v_mul_f32_e32 v111, v111, v98
	v_mul_f32_e32 v112, v112, v99
	v_cvt_pk_bf16_f32 v37, v111, v112
	v_lshlrev_b32_e32 v111, 16, v38
	v_and_b32_e32 v112, 0xffff0000, v38
	v_mul_f32_e32 v111, s41, v111
	v_mul_f32_e32 v112, s41, v112
	v_mul_f32_e32 v111, v111, v100
	v_mul_f32_e32 v112, v112, v101
	v_cvt_pk_bf16_f32 v38, v111, v112
	v_lshlrev_b32_e32 v111, 16, v39
	v_and_b32_e32 v112, 0xffff0000, v39
	v_mul_f32_e32 v111, s41, v111
	v_mul_f32_e32 v112, s41, v112
	v_mul_f32_e32 v111, v111, v102
	v_mul_f32_e32 v112, v112, v103
	v_cvt_pk_bf16_f32 v39, v111, v112
	global_store_dwordx4 v110, v[36:39], s[44:45] offset:3072
	s_mov_b32 s35, s28
	s_cmp_ge_u32 s35, 0x6000
	s_cbranch_scc1 .Lon_done
; __device__ __forceinline__ float bf_lo(unsigned w) { return __uint_as_float(w << 16); }
; __device__ __forceinline__ float bf_hi(unsigned w) { return __uint_as_float(w & 0xffff0000u); }
; __device__ __forceinline__ void outnorm_rows(bf16_t* y, const float* og, int bx, int G) {
;     ...
;     for (int row = (bx * 8 + wave) * 2; row < T; row += G * 16) {
;         u32x4 w[2][4]; float ss[2][3];
; #pragma unroll
;         for (int rr = 0; rr < 2; ++rr)
; #pragma unroll
;             for (int it = 0; it < 4; ++it) w[rr][it] = *(const u32x4*)(y + (size_t)(row + rr) * 2048 + (it * 64 + lane) * 8);
; #pragma unroll
;         for (int rr = 0; rr < 2; ++rr) { ss[rr][0] = 0.f; ss[rr][1] = 0.f; ss[rr][2] = 0.f;
; #pragma unroll
;             for (int it = 0; it < 4; ++it) { const int ch = it * 64 + lane; float s = 0.f;
; #pragma unroll
;                 for (int q = 0; q < 4; ++q) { const float a0 = bf_lo(w[rr][it][q]), a1 = bf_hi(w[rr][it][q]); s += a0 * a0 + a1 * a1; }
;                 const int seg = ch < 96 ? 0 : (ch < 160 ? 1 : 2);
;                 ss[rr][0] += seg == 0 ? s : 0.f; ss[rr][1] += seg == 1 ? s : 0.f; ss[rr][2] += seg == 2 ? s : 0.f; }
;             ss[rr][0] = wave_sum(ss[rr][0]); ss[rr][1] = wave_sum(ss[rr][1]); ss[rr][2] = wave_sum(ss[rr][2]); }
	s_add_i32 s28, s35, s34
	s_cmp_lt_u32 s28, 0x6000
	s_cselect_b32 s29, s28, s35
	v_lshl_add_u32 v7, s29, 12, v4
	v_add_u32_e32 v110, 0x1000, v7
	global_load_dwordx4 v[8:11], v7, s[44:45]
	global_load_dwordx4 v[12:15], v7, s[44:45] offset:1024
	global_load_dwordx4 v[16:19], v7, s[44:45] offset:2048
	global_load_dwordx4 v[20:23], v7, s[44:45] offset:3072
	global_load_dwordx4 v[24:27], v110, s[44:45]
	global_load_dwordx4 v[28:31], v110, s[44:45] offset:1024
	global_load_dwordx4 v[32:35], v110, s[44:45] offset:2048
	global_load_dwordx4 v[36:39], v110, s[44:45] offset:3072
	s_waitcnt vmcnt(8)
	v_lshlrev_b32_e32 v111, 16, v40
	v_and_b32_e32 v112, 0xffff0000, v40
	v_mul_f32_e32 v113, v111, v111
	v_fmac_f32_e32 v113, v112, v112
	v_lshlrev_b32_e32 v111, 16, v41
	v_and_b32_e32 v112, 0xffff0000, v41
	v_fmac_f32_e32 v113, v111, v111
	v_fmac_f32_e32 v113, v112, v112
	v_lshlrev_b32_e32 v111, 16, v42
	v_and_b32_e32 v112, 0xffff0000, v42
	v_fmac_f32_e32 v113, v111, v111
	v_fmac_f32_e32 v113, v112, v112
	v_lshlrev_b32_e32 v111, 16, v43
	v_and_b32_e32 v112, 0xffff0000, v43
	v_fmac_f32_e32 v113, v111, v111
	v_fmac_f32_e32 v113, v112, v112
	v_lshlrev_b32_e32 v111, 16, v44
	v_and_b32_e32 v112, 0xffff0000, v44
	v_mul_f32_e32 v114, v111, v111
	v_fmac_f32_e32 v114, v112, v112
	v_lshlrev_b32_e32 v111, 16, v45
	v_and_b32_e32 v112, 0xffff0000, v45
	v_fmac_f32_e32 v114, v111, v111
	v_fmac_f32_e32 v114, v112, v112
	v_lshlrev_b32_e32 v111, 16, v46
	v_and_b32_e32 v112, 0xffff0000, v46
	v_fmac_f32_e32 v114, v111, v111
	v_fmac_f32_e32 v114, v112, v112
	v_lshlrev_b32_e32 v111, 16, v47
	v_and_b32_e32 v112, 0xffff0000, v47
	v_fmac_f32_e32 v114, v111, v111
	v_fmac_f32_e32 v114, v112, v112
	v_lshlrev_b32_e32 v111, 16, v48
	v_and_b32_e32 v112, 0xffff0000, v48
	v_mul_f32_e32 v115, v111, v111
	v_fmac_f32_e32 v115, v112, v112
	v_lshlrev_b32_e32 v111, 16, v49
	v_and_b32_e32 v112, 0xffff0000, v49
	v_fmac_f32_e32 v115, v111, v111
	v_fmac_f32_e32 v115, v112, v112
	v_lshlrev_b32_e32 v111, 16, v50
	v_and_b32_e32 v112, 0xffff0000, v50
	v_fmac_f32_e32 v115, v111, v111
	v_fmac_f32_e32 v115, v112, v112
	v_lshlrev_b32_e32 v111, 16, v51
	v_and_b32_e32 v112, 0xffff0000, v51
	v_fmac_f32_e32 v115, v111, v111
	v_fmac_f32_e32 v115, v112, v112
	v_lshlrev_b32_e32 v111, 16, v52
	v_and_b32_e32 v112, 0xffff0000, v52
	v_mul_f32_e32 v116, v111, v111
	v_fmac_f32_e32 v116, v112, v112
	v_lshlrev_b32_e32 v111, 16, v53
	v_and_b32_e32 v112, 0xffff0000, v53
	v_fmac_f32_e32 v116, v111, v111
	v_fmac_f32_e32 v116, v112, v112
	v_lshlrev_b32_e32 v111, 16, v54
	v_and_b32_e32 v112, 0xffff0000, v54
	v_fmac_f32_e32 v116, v111, v111
	v_fmac_f32_e32 v116, v112, v112
	v_lshlrev_b32_e32 v111, 16, v55
	v_and_b32_e32 v112, 0xffff0000, v55
	v_fmac_f32_e32 v116, v111, v111
	v_fmac_f32_e32 v116, v112, v112
	v_cndmask_b32_e64 v111, 0, v114, s[48:49]
	v_sub_f32_e32 v112, v114, v111
	v_add_f32_e32 v117, v113, v111
	v_cndmask_b32_e64 v111, 0, v115, s[48:49]
	v_add_f32_e32 v118, v112, v111
	v_sub_f32_e32 v111, v115, v111
	v_add_f32_e32 v119, v111, v116
	v_lshlrev_b32_e32 v111, 16, v56
	v_and_b32_e32 v112, 0xffff0000, v56
	v_mul_f32_e32 v113, v111, v111
	v_fmac_f32_e32 v113, v112, v112
	v_lshlrev_b32_e32 v111, 16, v57
	v_and_b32_e32 v112, 0xffff0000, v57
	v_fmac_f32_e32 v113, v111, v111
	v_fmac_f32_e32 v113, v112, v112
	v_lshlrev_b32_e32 v111, 16, v58
	v_and_b32_e32 v112, 0xffff0000, v58
	v_fmac_f32_e32 v113, v111, v111
	v_fmac_f32_e32 v113, v112, v112
	v_lshlrev_b32_e32 v111, 16, v59
	v_and_b32_e32 v112, 0xffff0000, v59
	v_fmac_f32_e32 v113, v111, v111
	v_fmac_f32_e32 v113, v112, v112
	v_lshlrev_b32_e32 v111, 16, v60
	v_and_b32_e32 v112, 0xffff0000, v60
	v_mul_f32_e32 v114, v111, v111
	v_fmac_f32_e32 v114, v112, v112
	v_lshlrev_b32_e32 v111, 16, v61
	v_and_b32_e32 v112, 0xffff0000, v61
	v_fmac_f32_e32 v114, v111, v111
	v_fmac_f32_e32 v114, v112, v112
	v_lshlrev_b32_e32 v111, 16, v62
	v_and_b32_e32 v112, 0xffff0000, v62
	v_fmac_f32_e32 v114, v111, v111
	v_fmac_f32_e32 v114, v112, v112
	v_lshlrev_b32_e32 v111, 16, v63
	v_and_b32_e32 v112, 0xffff0000, v63
	v_fmac_f32_e32 v114, v111, v111
	v_fmac_f32_e32 v114, v112, v112
	v_lshlrev_b32_e32 v111, 16, v64
	v_and_b32_e32 v112, 0xffff0000, v64
	v_mul_f32_e32 v115, v111, v111
	v_fmac_f32_e32 v115, v112, v112
	v_lshlrev_b32_e32 v111, 16, v65
	v_and_b32_e32 v112, 0xffff0000, v65
	v_fmac_f32_e32 v115, v111, v111
	v_fmac_f32_e32 v115, v112, v112
	v_lshlrev_b32_e32 v111, 16, v66
	v_and_b32_e32 v112, 0xffff0000, v66
	v_fmac_f32_e32 v115, v111, v111
	v_fmac_f32_e32 v115, v112, v112
	v_lshlrev_b32_e32 v111, 16, v67
	v_and_b32_e32 v112, 0xffff0000, v67
	v_fmac_f32_e32 v115, v111, v111
	v_fmac_f32_e32 v115, v112, v112
	v_lshlrev_b32_e32 v111, 16, v68
	v_and_b32_e32 v112, 0xffff0000, v68
	v_mul_f32_e32 v116, v111, v111
	v_fmac_f32_e32 v116, v112, v112
	v_lshlrev_b32_e32 v111, 16, v69
	v_and_b32_e32 v112, 0xffff0000, v69
	v_fmac_f32_e32 v116, v111, v111
	v_fmac_f32_e32 v116, v112, v112
	v_lshlrev_b32_e32 v111, 16, v70
	v_and_b32_e32 v112, 0xffff0000, v70
	v_fmac_f32_e32 v116, v111, v111
	v_fmac_f32_e32 v116, v112, v112
	v_lshlrev_b32_e32 v111, 16, v71
	v_and_b32_e32 v112, 0xffff0000, v71
	v_fmac_f32_e32 v116, v111, v111
	v_fmac_f32_e32 v116, v112, v112
	v_cndmask_b32_e64 v111, 0, v114, s[48:49]
	v_sub_f32_e32 v112, v114, v111
	v_add_f32_e32 v120, v113, v111
	v_cndmask_b32_e64 v111, 0, v115, s[48:49]
	v_add_f32_e32 v121, v112, v111
	v_sub_f32_e32 v111, v115, v111
	v_add_f32_e32 v122, v111, v116
	ds_bpermute_b32 v123, v104, v117
	ds_bpermute_b32 v124, v104, v118
	ds_bpermute_b32 v125, v104, v119
	ds_bpermute_b32 v126, v104, v120
	ds_bpermute_b32 v127, v104, v121
	ds_bpermute_b32 v2, v104, v122
	s_waitcnt lgkmcnt(0)
; __device__ __forceinline__ unsigned cvt_pk_bf16(float lo, float hi) { unsigned r; asm("v_cvt_pk_bf16_f32 %0, %1, %2" : "=v"(r) : "v"(lo), "v"(hi)); return r; }
; __device__ __forceinline__ float bf_lo(unsigned w) { return __uint_as_float(w << 16); }
; __device__ __forceinline__ float bf_hi(unsigned w) { return __uint_as_float(w & 0xffff0000u); }
; __device__ __forceinline__ void outnorm_rows(bf16_t* y, const float* og, int bx, int G) {
;     ...
;         for (int rr = 0; rr < 2; ++rr) { ss[rr][0] = 0.f; ss[rr][1] = 0.f; ss[rr][2] = 0.f;
; #pragma unroll
;             for (int it = 0; it < 4; ++it) { const int ch = it * 64 + lane; float s = 0.f;
; #pragma unroll
;                 for (int q = 0; q < 4; ++q) { const float a0 = bf_lo(w[rr][it][q]), a1 = bf_hi(w[rr][it][q]); s += a0 * a0 + a1 * a1; }
;                 const int seg = ch < 96 ? 0 : (ch < 160 ? 1 : 2);
;                 ss[rr][0] += seg == 0 ? s : 0.f; ss[rr][1] += seg == 1 ? s : 0.f; ss[rr][2] += seg == 2 ? s : 0.f; }
;             ss[rr][0] = wave_sum(ss[rr][0]); ss[rr][1] = wave_sum(ss[rr][1]); ss[rr][2] = wave_sum(ss[rr][2]); }
; #pragma unroll
;         for (int rr = 0; rr < 2; ++rr) {
;             const float r0 = 1.0f / sqrtf(ss[rr][0] * (1.0f / 768.0f) + EPS), r1 = 1.0f / sqrtf(ss[rr][1] * (1.0f / 512.0f) + EPS), r2 = 1.0f / sqrtf(ss[rr][2] * (1.0f / 768.0f) + EPS);
; #pragma unroll
;             for (int it = 0; it < 4; ++it) { const int ch = it * 64 + lane; const float r = ch < 96 ? r0 : (ch < 160 ? r1 : r2);
;                 const f32x4 g0 = *(const f32x4*)(og + ch * 8), g1 = *(const f32x4*)(og + ch * 8 + 4);
;                 const u32x4 ww = w[rr][it];
;                 u32x4 o; o.x = cvt_pk_bf16(bf_lo(ww.x) * r * g0[0], bf_hi(ww.x) * r * g0[1]); o.y = cvt_pk_bf16(bf_lo(ww.y) * r * g0[2], bf_hi(ww.y) * r * g0[3]);
;                 o.z = cvt_pk_bf16(bf_lo(ww.z) * r * g1[0], bf_hi(ww.z) * r * g1[1]); o.w = cvt_pk_bf16(bf_lo(ww.w) * r * g1[2], bf_hi(ww.w) * r * g1[3]);
;                 *(u32x4*)(y + (size_t)(row + rr) * 2048 + ch * 8) = o; } }
	v_add_f32_e32 v117, v117, v123
	v_add_f32_e32 v118, v118, v124
	v_add_f32_e32 v119, v119, v125
	v_add_f32_e32 v120, v120, v126
	v_add_f32_e32 v121, v121, v127
	v_add_f32_e32 v122, v122, v2
	ds_bpermute_b32 v123, v105, v117
	ds_bpermute_b32 v124, v105, v118
	ds_bpermute_b32 v125, v105, v119
	ds_bpermute_b32 v126, v105, v120
	ds_bpermute_b32 v127, v105, v121
	ds_bpermute_b32 v2, v105, v122
	s_waitcnt lgkmcnt(0)
	v_add_f32_e32 v117, v117, v123
	v_add_f32_e32 v118, v118, v124
	v_add_f32_e32 v119, v119, v125
	v_add_f32_e32 v120, v120, v126
	v_add_f32_e32 v121, v121, v127
	v_add_f32_e32 v122, v122, v2
	ds_bpermute_b32 v123, v106, v117
	ds_bpermute_b32 v124, v106, v118
	ds_bpermute_b32 v125, v106, v119
	ds_bpermute_b32 v126, v106, v120
	ds_bpermute_b32 v127, v106, v121
	ds_bpermute_b32 v2, v106, v122
	s_waitcnt lgkmcnt(0)
	v_add_f32_e32 v117, v117, v123
	v_add_f32_e32 v118, v118, v124
	v_add_f32_e32 v119, v119, v125
	v_add_f32_e32 v120, v120, v126
	v_add_f32_e32 v121, v121, v127
	v_add_f32_e32 v122, v122, v2
	ds_bpermute_b32 v123, v107, v117
	ds_bpermute_b32 v124, v107, v118
	ds_bpermute_b32 v125, v107, v119
	ds_bpermute_b32 v126, v107, v120
	ds_bpermute_b32 v127, v107, v121
	ds_bpermute_b32 v2, v107, v122
	s_waitcnt lgkmcnt(0)
	v_add_f32_e32 v117, v117, v123
	v_add_f32_e32 v118, v118, v124
	v_add_f32_e32 v119, v119, v125
	v_add_f32_e32 v120, v120, v126
	v_add_f32_e32 v121, v121, v127
	v_add_f32_e32 v122, v122, v2
	ds_bpermute_b32 v123, v108, v117
	ds_bpermute_b32 v124, v108, v118
	ds_bpermute_b32 v125, v108, v119
	ds_bpermute_b32 v126, v108, v120
	ds_bpermute_b32 v127, v108, v121
	ds_bpermute_b32 v2, v108, v122
	s_waitcnt lgkmcnt(0)
	v_add_f32_e32 v117, v117, v123
	v_add_f32_e32 v118, v118, v124
	v_add_f32_e32 v119, v119, v125
	v_add_f32_e32 v120, v120, v126
	v_add_f32_e32 v121, v121, v127
	v_add_f32_e32 v122, v122, v2
	ds_bpermute_b32 v123, v109, v117
	ds_bpermute_b32 v124, v109, v118
	ds_bpermute_b32 v125, v109, v119
	ds_bpermute_b32 v126, v109, v120
	ds_bpermute_b32 v127, v109, v121
	ds_bpermute_b32 v2, v109, v122
	s_waitcnt lgkmcnt(0)
	v_add_f32_e32 v117, v117, v123
	v_add_f32_e32 v118, v118, v124
	v_add_f32_e32 v119, v119, v125
	v_add_f32_e32 v120, v120, v126
	v_add_f32_e32 v121, v121, v127
	v_add_f32_e32 v122, v122, v2
	v_fmamk_f32 v117, v117, 0x3aaaaaab, v222
	v_fmamk_f32 v118, v118, 0x3b000000, v222
	v_fmamk_f32 v119, v119, 0x3aaaaaab, v222
	v_fmamk_f32 v120, v120, 0x3aaaaaab, v222
	v_fmamk_f32 v121, v121, 0x3b000000, v222
	v_fmamk_f32 v122, v122, 0x3aaaaaab, v222
	v_mov_b32_e32 v111, v117
	v_cmp_eq_u32_e32 vcc, 1, v1
	s_nop 1
	v_cndmask_b32_e32 v111, v111, v118, vcc
	v_cmp_eq_u32_e32 vcc, 2, v1
	s_nop 1
	v_cndmask_b32_e32 v111, v111, v119, vcc
	v_cmp_eq_u32_e32 vcc, 3, v1
	s_nop 1
	v_cndmask_b32_e32 v111, v111, v120, vcc
	v_cmp_eq_u32_e32 vcc, 4, v1
	s_nop 1
	v_cndmask_b32_e32 v111, v111, v121, vcc
	v_cmp_eq_u32_e32 vcc, 5, v1
	s_nop 1
	v_cndmask_b32_e32 v111, v111, v122, vcc
	v_cmp_gt_f32_e32 vcc, s89, v111
	v_mul_f32_e32 v112, 0x4f800000, v111
	s_nop 0
	v_cndmask_b32_e32 v111, v111, v112, vcc
	v_sqrt_f32_e32 v112, v111
	s_nop 0
	v_add_u32_e32 v113, -1, v112
	v_fma_f32 v114, -v113, v112, v111
	v_cmp_ge_f32_e64 s[50:51], 0, v114
	v_add_u32_e32 v114, 1, v112
	s_nop 0
	v_cndmask_b32_e64 v113, v112, v113, s[50:51]
	v_fma_f32 v112, -v114, v112, v111
	v_cmp_lt_f32_e64 s[50:51], 0, v112
	s_nop 1
	v_cndmask_b32_e64 v112, v113, v114, s[50:51]
	v_mul_f32_e32 v113, 0x37800000, v112
	v_cndmask_b32_e32 v112, v112, v113, vcc
	v_cmp_class_f32_e32 vcc, v111, v223
	s_nop 1
	v_cndmask_b32_e32 v111, v112, v111, vcc
	v_div_scale_f32 v112, s[50:51], v111, v111, 1.0
	v_rcp_f32_e32 v113, v112
	s_nop 0
	v_fma_f32 v114, -v112, v113, 1.0
	v_fmac_f32_e32 v113, v114, v113
	v_div_scale_f32 v114, vcc, 1.0, v111, 1.0
	v_mul_f32_e32 v115, v114, v113
	v_fma_f32 v116, -v112, v115, v114
	v_fmac_f32_e32 v115, v116, v113
	v_fma_f32 v112, -v112, v115, v114
	v_div_fmas_f32 v112, v112, v113, v115
	v_div_fixup_f32 v123, v112, v111, 1.0
	s_nop 1
	v_readlane_b32 s36, v123, 0
	v_readlane_b32 s37, v123, 1
	v_readlane_b32 s38, v123, 2
	v_readlane_b32 s39, v123, 3
	v_readlane_b32 s40, v123, 4
	v_readlane_b32 s41, v123, 5
	s_nop 3
	v_mov_b32_e32 v124, s37
	v_mov_b32_e32 v126, s36
	v_cndmask_b32_e64 v124, v124, v126, s[48:49]
	v_mov_b32_e32 v125, s38
	v_mov_b32_e32 v126, s37
	v_cndmask_b32_e64 v125, v125, v126, s[48:49]
	v_lshlrev_b32_e32 v111, 16, v40
	v_and_b32_e32 v112, 0xffff0000, v40
	v_mul_f32_e32 v111, s36, v111
	v_mul_f32_e32 v112, s36, v112
	v_mul_f32_e32 v111, v111, v72
	v_mul_f32_e32 v112, v112, v73
	v_cvt_pk_bf16_f32 v40, v111, v112
	v_lshlrev_b32_e32 v111, 16, v41
	v_and_b32_e32 v112, 0xffff0000, v41
	v_mul_f32_e32 v111, s36, v111
	v_mul_f32_e32 v112, s36, v112
	v_mul_f32_e32 v111, v111, v74
	v_mul_f32_e32 v112, v112, v75
	v_cvt_pk_bf16_f32 v41, v111, v112
	v_lshlrev_b32_e32 v111, 16, v42
	v_and_b32_e32 v112, 0xffff0000, v42
	v_mul_f32_e32 v111, s36, v111
	v_mul_f32_e32 v112, s36, v112
	v_mul_f32_e32 v111, v111, v76
	v_mul_f32_e32 v112, v112, v77
	v_cvt_pk_bf16_f32 v42, v111, v112
	v_lshlrev_b32_e32 v111, 16, v43
	v_and_b32_e32 v112, 0xffff0000, v43
	v_mul_f32_e32 v111, s36, v111
	v_mul_f32_e32 v112, s36, v112
	v_mul_f32_e32 v111, v111, v78
	v_mul_f32_e32 v112, v112, v79
	v_cvt_pk_bf16_f32 v43, v111, v112
	global_store_dwordx4 v5, v[40:43], s[44:45]
	v_lshlrev_b32_e32 v111, 16, v44
	v_and_b32_e32 v112, 0xffff0000, v44
	v_mul_f32_e32 v111, v124, v111
	v_mul_f32_e32 v112, v124, v112
	v_mul_f32_e32 v111, v111, v80
	v_mul_f32_e32 v112, v112, v81
	v_cvt_pk_bf16_f32 v44, v111, v112
	v_lshlrev_b32_e32 v111, 16, v45
	v_and_b32_e32 v112, 0xffff0000, v45
	v_mul_f32_e32 v111, v124, v111
; __device__ __forceinline__ unsigned cvt_pk_bf16(float lo, float hi) { unsigned r; asm("v_cvt_pk_bf16_f32 %0, %1, %2" : "=v"(r) : "v"(lo), "v"(hi)); return r; }
; __device__ __forceinline__ float bf_lo(unsigned w) { return __uint_as_float(w << 16); }
; __device__ __forceinline__ float bf_hi(unsigned w) { return __uint_as_float(w & 0xffff0000u); }
; __device__ __forceinline__ void outnorm_rows(bf16_t* y, const float* og, int bx, int G) {
;     ...
;         for (int rr = 0; rr < 2; ++rr) {
;             const float r0 = 1.0f / sqrtf(ss[rr][0] * (1.0f / 768.0f) + EPS), r1 = 1.0f / sqrtf(ss[rr][1] * (1.0f / 512.0f) + EPS), r2 = 1.0f / sqrtf(ss[rr][2] * (1.0f / 768.0f) + EPS);
; #pragma unroll
;             for (int it = 0; it < 4; ++it) { const int ch = it * 64 + lane; const float r = ch < 96 ? r0 : (ch < 160 ? r1 : r2);
;                 const f32x4 g0 = *(const f32x4*)(og + ch * 8), g1 = *(const f32x4*)(og + ch * 8 + 4);
;                 const u32x4 ww = w[rr][it];
;                 u32x4 o; o.x = cvt_pk_bf16(bf_lo(ww.x) * r * g0[0], bf_hi(ww.x) * r * g0[1]); o.y = cvt_pk_bf16(bf_lo(ww.y) * r * g0[2], bf_hi(ww.y) * r * g0[3]);
;                 o.z = cvt_pk_bf16(bf_lo(ww.z) * r * g1[0], bf_hi(ww.z) * r * g1[1]); o.w = cvt_pk_bf16(bf_lo(ww.w) * r * g1[2], bf_hi(ww.w) * r * g1[3]);
;                 *(u32x4*)(y + (size_t)(row + rr) * 2048 + ch * 8) = o; } }
	v_mul_f32_e32 v112, v124, v112
	v_mul_f32_e32 v111, v111, v82
	v_mul_f32_e32 v112, v112, v83
	v_cvt_pk_bf16_f32 v45, v111, v112
	v_lshlrev_b32_e32 v111, 16, v46
	v_and_b32_e32 v112, 0xffff0000, v46
	v_mul_f32_e32 v111, v124, v111
	v_mul_f32_e32 v112, v124, v112
	v_mul_f32_e32 v111, v111, v84
	v_mul_f32_e32 v112, v112, v85
	v_cvt_pk_bf16_f32 v46, v111, v112
	v_lshlrev_b32_e32 v111, 16, v47
	v_and_b32_e32 v112, 0xffff0000, v47
	v_mul_f32_e32 v111, v124, v111
	v_mul_f32_e32 v112, v124, v112
	v_mul_f32_e32 v111, v111, v86
	v_mul_f32_e32 v112, v112, v87
	v_cvt_pk_bf16_f32 v47, v111, v112
	global_store_dwordx4 v5, v[44:47], s[44:45] offset:1024
	v_lshlrev_b32_e32 v111, 16, v48
	v_and_b32_e32 v112, 0xffff0000, v48
	v_mul_f32_e32 v111, v125, v111
	v_mul_f32_e32 v112, v125, v112
	v_mul_f32_e32 v111, v111, v88
	v_mul_f32_e32 v112, v112, v89
	v_cvt_pk_bf16_f32 v48, v111, v112
	v_lshlrev_b32_e32 v111, 16, v49
	v_and_b32_e32 v112, 0xffff0000, v49
	v_mul_f32_e32 v111, v125, v111
	v_mul_f32_e32 v112, v125, v112
	v_mul_f32_e32 v111, v111, v90
	v_mul_f32_e32 v112, v112, v91
	v_cvt_pk_bf16_f32 v49, v111, v112
	v_lshlrev_b32_e32 v111, 16, v50
	v_and_b32_e32 v112, 0xffff0000, v50
	v_mul_f32_e32 v111, v125, v111
	v_mul_f32_e32 v112, v125, v112
	v_mul_f32_e32 v111, v111, v92
	v_mul_f32_e32 v112, v112, v93
	v_cvt_pk_bf16_f32 v50, v111, v112
	v_lshlrev_b32_e32 v111, 16, v51
	v_and_b32_e32 v112, 0xffff0000, v51
	v_mul_f32_e32 v111, v125, v111
	v_mul_f32_e32 v112, v125, v112
	v_mul_f32_e32 v111, v111, v94
	v_mul_f32_e32 v112, v112, v95
	v_cvt_pk_bf16_f32 v51, v111, v112
	global_store_dwordx4 v5, v[48:51], s[44:45] offset:2048
	v_lshlrev_b32_e32 v111, 16, v52
	v_and_b32_e32 v112, 0xffff0000, v52
	v_mul_f32_e32 v111, s38, v111
	v_mul_f32_e32 v112, s38, v112
	v_mul_f32_e32 v111, v111, v96
	v_mul_f32_e32 v112, v112, v97
	v_cvt_pk_bf16_f32 v52, v111, v112
	v_lshlrev_b32_e32 v111, 16, v53
	v_and_b32_e32 v112, 0xffff0000, v53
	v_mul_f32_e32 v111, s38, v111
	v_mul_f32_e32 v112, s38, v112
	v_mul_f32_e32 v111, v111, v98
	v_mul_f32_e32 v112, v112, v99
	v_cvt_pk_bf16_f32 v53, v111, v112
	v_lshlrev_b32_e32 v111, 16, v54
	v_and_b32_e32 v112, 0xffff0000, v54
	v_mul_f32_e32 v111, s38, v111
	v_mul_f32_e32 v112, s38, v112
	v_mul_f32_e32 v111, v111, v100
	v_mul_f32_e32 v112, v112, v101
	v_cvt_pk_bf16_f32 v54, v111, v112
	v_lshlrev_b32_e32 v111, 16, v55
	v_and_b32_e32 v112, 0xffff0000, v55
	v_mul_f32_e32 v111, s38, v111
	v_mul_f32_e32 v112, s38, v112
	v_mul_f32_e32 v111, v111, v102
	v_mul_f32_e32 v112, v112, v103
	v_cvt_pk_bf16_f32 v55, v111, v112
	global_store_dwordx4 v5, v[52:55], s[44:45] offset:3072
	v_mov_b32_e32 v124, s40
	v_mov_b32_e32 v126, s39
	v_cndmask_b32_e64 v124, v124, v126, s[48:49]
	v_mov_b32_e32 v125, s41
	v_mov_b32_e32 v126, s40
	v_cndmask_b32_e64 v125, v125, v126, s[48:49]
	v_lshlrev_b32_e32 v111, 16, v56
	v_and_b32_e32 v112, 0xffff0000, v56
	v_mul_f32_e32 v111, s39, v111
	v_mul_f32_e32 v112, s39, v112
	v_mul_f32_e32 v111, v111, v72
	v_mul_f32_e32 v112, v112, v73
	v_cvt_pk_bf16_f32 v56, v111, v112
	v_lshlrev_b32_e32 v111, 16, v57
	v_and_b32_e32 v112, 0xffff0000, v57
	v_mul_f32_e32 v111, s39, v111
	v_mul_f32_e32 v112, s39, v112
	v_mul_f32_e32 v111, v111, v74
	v_mul_f32_e32 v112, v112, v75
	v_cvt_pk_bf16_f32 v57, v111, v112
	v_lshlrev_b32_e32 v111, 16, v58
	v_and_b32_e32 v112, 0xffff0000, v58
	v_mul_f32_e32 v111, s39, v111
	v_mul_f32_e32 v112, s39, v112
	v_mul_f32_e32 v111, v111, v76
	v_mul_f32_e32 v112, v112, v77
	v_cvt_pk_bf16_f32 v58, v111, v112
	v_lshlrev_b32_e32 v111, 16, v59
	v_and_b32_e32 v112, 0xffff0000, v59
	v_mul_f32_e32 v111, s39, v111
	v_mul_f32_e32 v112, s39, v112
	v_mul_f32_e32 v111, v111, v78
	v_mul_f32_e32 v112, v112, v79
	v_cvt_pk_bf16_f32 v59, v111, v112
	global_store_dwordx4 v6, v[56:59], s[44:45]
	v_lshlrev_b32_e32 v111, 16, v60
	v_and_b32_e32 v112, 0xffff0000, v60
	v_mul_f32_e32 v111, v124, v111
	v_mul_f32_e32 v112, v124, v112
	v_mul_f32_e32 v111, v111, v80
	v_mul_f32_e32 v112, v112, v81
	v_cvt_pk_bf16_f32 v60, v111, v112
	v_lshlrev_b32_e32 v111, 16, v61
	v_and_b32_e32 v112, 0xffff0000, v61
	v_mul_f32_e32 v111, v124, v111
	v_mul_f32_e32 v112, v124, v112
	v_mul_f32_e32 v111, v111, v82
	v_mul_f32_e32 v112, v112, v83
	v_cvt_pk_bf16_f32 v61, v111, v112
	v_lshlrev_b32_e32 v111, 16, v62
	v_and_b32_e32 v112, 0xffff0000, v62
	v_mul_f32_e32 v111, v124, v111
	v_mul_f32_e32 v112, v124, v112
	v_mul_f32_e32 v111, v111, v84
	v_mul_f32_e32 v112, v112, v85
	v_cvt_pk_bf16_f32 v62, v111, v112
	v_lshlrev_b32_e32 v111, 16, v63
	v_and_b32_e32 v112, 0xffff0000, v63
	v_mul_f32_e32 v111, v124, v111
	v_mul_f32_e32 v112, v124, v112
	v_mul_f32_e32 v111, v111, v86
	v_mul_f32_e32 v112, v112, v87
	v_cvt_pk_bf16_f32 v63, v111, v112
	global_store_dwordx4 v6, v[60:63], s[44:45] offset:1024
	v_lshlrev_b32_e32 v111, 16, v64
	v_and_b32_e32 v112, 0xffff0000, v64
	v_mul_f32_e32 v111, v125, v111
	v_mul_f32_e32 v112, v125, v112
	v_mul_f32_e32 v111, v111, v88
	v_mul_f32_e32 v112, v112, v89
	v_cvt_pk_bf16_f32 v64, v111, v112
	v_lshlrev_b32_e32 v111, 16, v65
	v_and_b32_e32 v112, 0xffff0000, v65
	v_mul_f32_e32 v111, v125, v111
	v_mul_f32_e32 v112, v125, v112
	v_mul_f32_e32 v111, v111, v90
	v_mul_f32_e32 v112, v112, v91
	v_cvt_pk_bf16_f32 v65, v111, v112
	v_lshlrev_b32_e32 v111, 16, v66
	v_and_b32_e32 v112, 0xffff0000, v66
	v_mul_f32_e32 v111, v125, v111
	v_mul_f32_e32 v112, v125, v112
	v_mul_f32_e32 v111, v111, v92
	v_mul_f32_e32 v112, v112, v93
	v_cvt_pk_bf16_f32 v66, v111, v112
	v_lshlrev_b32_e32 v111, 16, v67
	v_and_b32_e32 v112, 0xffff0000, v67
	v_mul_f32_e32 v111, v125, v111
	v_mul_f32_e32 v112, v125, v112
	v_mul_f32_e32 v111, v111, v94
	v_mul_f32_e32 v112, v112, v95
	v_cvt_pk_bf16_f32 v67, v111, v112
	global_store_dwordx4 v6, v[64:67], s[44:45] offset:2048
	v_lshlrev_b32_e32 v111, 16, v68
	v_and_b32_e32 v112, 0xffff0000, v68
	v_mul_f32_e32 v111, s41, v111
	v_mul_f32_e32 v112, s41, v112
	v_mul_f32_e32 v111, v111, v96
	v_mul_f32_e32 v112, v112, v97
	v_cvt_pk_bf16_f32 v68, v111, v112
	v_lshlrev_b32_e32 v111, 16, v69
	v_and_b32_e32 v112, 0xffff0000, v69
	v_mul_f32_e32 v111, s41, v111
	v_mul_f32_e32 v112, s41, v112
	v_mul_f32_e32 v111, v111, v98
	v_mul_f32_e32 v112, v112, v99
	v_cvt_pk_bf16_f32 v69, v111, v112
	v_lshlrev_b32_e32 v111, 16, v70
	v_and_b32_e32 v112, 0xffff0000, v70
	v_mul_f32_e32 v111, s41, v111
	v_mul_f32_e32 v112, s41, v112
	v_mul_f32_e32 v111, v111, v100
	v_mul_f32_e32 v112, v112, v101
	v_cvt_pk_bf16_f32 v70, v111, v112
	v_lshlrev_b32_e32 v111, 16, v71
	v_and_b32_e32 v112, 0xffff0000, v71
	v_mul_f32_e32 v111, s41, v111
	v_mul_f32_e32 v112, s41, v112
	v_mul_f32_e32 v111, v111, v102
	v_mul_f32_e32 v112, v112, v103
	v_cvt_pk_bf16_f32 v71, v111, v112
	global_store_dwordx4 v6, v[68:71], s[44:45] offset:3072
	s_mov_b32 s35, s28
	s_cmp_lt_u32 s35, 0x6000
	s_cbranch_scc1 .Lon_loop
; __device__ __forceinline__ int tid_l() { int t = threadIdx.x; asm volatile("" : "+v"(t)); return t; }
; __device__ __forceinline__ float bf_lo(unsigned w) { return __uint_as_float(w << 16); }
; __device__ __forceinline__ float bf_hi(unsigned w) { return __uint_as_float(w & 0xffff0000u); }
; __device__ __forceinline__ void outnorm_rows(bf16_t* y, const float* og, int bx, int G) {
;     const int tid = tid_l(), lane = tid & 63, wave = tid >> 6;
;     for (int row = (bx * 8 + wave) * 2; row < T; row += G * 16) {
;         u32x4 w[2][4]; float ss[2][3];
; #pragma unroll
;         for (int rr = 0; rr < 2; ++rr)
; #pragma unroll
;             for (int it = 0; it < 4; ++it) w[rr][it] = *(const u32x4*)(y + (size_t)(row + rr) * 2048 + (it * 64 + lane) * 8);
; #pragma unroll
;         for (int rr = 0; rr < 2; ++rr) { ss[rr][0] = 0.f; ss[rr][1] = 0.f; ss[rr][2] = 0.f;
; #pragma unroll
;             for (int it = 0; it < 4; ++it) { const int ch = it * 64 + lane; float s = 0.f;
; #pragma unroll
;                 for (int q = 0; q < 4; ++q) { const float a0 = bf_lo(w[rr][it][q]), a1 = bf_hi(w[rr][it][q]); s += a0 * a0 + a1 * a1; }
;                 const int seg = ch < 96 ? 0 : (ch < 160 ? 1 : 2);
;                 ss[rr][0] += seg == 0 ? s : 0.f; ss[rr][1] += seg == 1 ? s : 0.f; ss[rr][2] += seg == 2 ? s : 0.f; }
;             ss[rr][0] = wave_sum(ss[rr][0]); ss[rr][1] = wave_sum(ss[rr][1]); ss[rr][2] = wave_sum(ss[rr][2]); }
.Lon_done:
	s_waitcnt vmcnt(0)
	v_readlane_b32 s0, v255, 24
	v_readlane_b32 s2, v255, 25
	v_readlane_b32 s28, v255, 26
	v_readlane_b32 s29, v255, 27
	v_readlane_b32 s33, v255, 28
	v_readlane_b32 s34, v255, 29
	v_readlane_b32 s35, v255, 30
	v_readlane_b32 s36, v255, 31
	v_readlane_b32 s37, v255, 32
	v_readlane_b32 s38, v255, 33
	v_readlane_b32 s39, v255, 34
	v_readlane_b32 s40, v255, 35
	v_readlane_b32 s41, v255, 36
	v_readlane_b32 s44, v255, 37
	v_readlane_b32 s45, v255, 38
	v_readlane_b32 s46, v255, 39
	v_readlane_b32 s47, v255, 44
	v_readlane_b32 s48, v255, 45
	v_readlane_b32 s49, v255, 46
	v_readlane_b32 s50, v255, 47
	v_readlane_b32 s51, v255, 48
	v_readlane_b32 s52, v255, 49
	v_readlane_b32 s53, v255, 50
	v_readlane_b32 s54, v255, 51
	v_readlane_b32 s55, v255, 52
	v_readlane_b32 s56, v255, 53
	v_readlane_b32 s57, v255, 54
	v_readlane_b32 s58, v255, 55
	v_readlane_b32 s59, v255, 56
	v_readlane_b32 s90, v255, 57
	v_readlane_b32 vcc_lo, v255, 58
	v_readlane_b32 vcc_hi, v255, 59
	s_nop 3
	v_ashrrev_i32_e32 v1, 5, v0
	v_and_b32_e32 v1, -2, v1
	v_lshl_add_u32 v20, s2, 4, v1
	s_movk_i32 s2, 0
	v_cmp_gt_i32_e32 vcc, s2, v20
	s_and_saveexec_b64 s[34:35], vcc
	s_cbranch_execz .LBB0_1159
	v_and_b32_e32 v2, 63, v0
	v_and_b32_e32 v0, 64, v177
	v_add_u32_e32 v0, 64, v0
	v_xor_b32_e32 v1, 32, v177
	v_cmp_lt_i32_e32 vcc, v1, v0
	s_lshl_b32 s90, s30, 11
	v_readlane_b32 s40, v253, 20
	v_cndmask_b32_e32 v1, v177, v1, vcc
	v_lshlrev_b32_e32 v42, 2, v1
	v_xor_b32_e32 v1, 16, v177
	v_cmp_lt_i32_e32 vcc, v1, v0
	s_lshl_b64 s[36:37], s[90:91], 2
	v_readlane_b32 s42, v253, 22
	v_cndmask_b32_e32 v1, v177, v1, vcc
	v_lshlrev_b32_e32 v43, 2, v1
	v_xor_b32_e32 v1, 8, v177
	v_cmp_lt_i32_e32 vcc, v1, v0
	v_readlane_b32 s50, v253, 30
	v_readlane_b32 s43, v253, 23
	v_cndmask_b32_e32 v1, v177, v1, vcc
	v_lshlrev_b32_e32 v44, 2, v1
	v_xor_b32_e32 v1, 4, v177
	v_cmp_lt_i32_e32 vcc, v1, v0
	v_readlane_b32 s51, v253, 31
	s_add_u32 s50, s42, s36
	v_cndmask_b32_e32 v1, v177, v1, vcc
	v_lshlrev_b32_e32 v45, 2, v1
	v_xor_b32_e32 v1, 2, v177
	v_cmp_lt_i32_e32 vcc, v1, v0
	s_addc_u32 s51, s43, s37
	s_lshl_b32 s36, s0, 4
	v_cndmask_b32_e32 v1, v177, v1, vcc
	v_lshlrev_b32_e32 v46, 2, v1
	v_xor_b32_e32 v1, 1, v177
	v_cmp_lt_i32_e32 vcc, v1, v0
	s_movk_i32 s0, 0x5f
	v_or_b32_e32 v3, 0x80, v2
	v_cndmask_b32_e32 v0, v177, v1, vcc
	v_lshlrev_b32_e32 v47, 2, v0
	v_or_b32_e32 v0, 64, v2
	v_cmp_lt_u32_e64 s[38:39], s0, v0
	s_movk_i32 s0, 0x9f
	v_readlane_b32 s46, v253, 26
	v_readlane_b32 s47, v253, 27
	v_cmp_lt_u32_e64 s[42:43], s0, v3
	s_movk_i32 s0, 0x60
	v_cmp_gt_u32_e64 s[46:47], s0, v0
	v_lshlrev_b32_e32 v0, 5, v0
	v_mov_b32_e32 v1, v173
	v_lshl_add_u64 v[24:25], s[50:51], 0, v[0:1]
	v_lshlrev_b32_e32 v0, 5, v3
	v_ashrrev_i32_e32 v21, 31, v20
	v_lshl_add_u64 v[26:27], s[50:51], 0, v[0:1]
	v_lshlrev_b64 v[0:1], 12, v[20:21]
	v_lshlrev_b32_e32 v172, 5, v2
	v_lshl_or_b32 v0, v2, 4, v0
	v_readlane_b32 s41, v253, 21
	v_readlane_b32 s44, v253, 24
	v_readlane_b32 s45, v253, 25
	v_readlane_b32 s48, v253, 28
	v_readlane_b32 s49, v253, 29
	v_lshl_add_u64 v[22:23], s[50:51], 0, v[172:173]
	s_movk_i32 s0, 0xa0
	v_or_b32_e32 v172, 0x1800, v172
	v_lshl_add_u64 v[0:1], s[28:29], 0, v[0:1]
	s_mov_b64 s[28:29], 0x9ce9c00
	s_ashr_i32 s37, s36, 31
	s_mov_b32 s90, 0x600000
	s_movk_i32 s2, 0xf000
	v_cmp_lt_u32_e64 s[40:41], 31, v2
	v_cmp_gt_u32_e64 s[44:45], 32, v2
	v_cmp_gt_u32_e64 s[48:49], s0, v3
	v_lshl_add_u64 v[28:29], s[50:51], 0, v[172:173]
	v_lshl_add_u64 v[30:31], v[0:1], 0, s[28:29]
	s_lshl_b64 s[28:29], s[36:37], 12
	s_mov_b64 s[92:93], 0
	v_readlane_b32 s52, v253, 32
	v_readlane_b32 s53, v253, 33
	v_readlane_b32 s54, v253, 34
	v_readlane_b32 s55, v253, 35
